# residual-GEMM K-loop (FFN-out, pool, O-proj): LDS-DMA staging rebalanced to 4 loads per phase
# baseline (speedup 1.0000x reference)
.LBB0_194:
	s_add_i32 s27, s30, 2
	s_add_u32 s33, s34, 0x80
	s_addc_u32 s31, s35, 0
	s_cmp_eq_u32 s90, s30
	s_cselect_b32 s31, s15, s31
	s_cselect_b32 s30, s14, s33
	s_cselect_b32 s45, s29, s4
	s_cselect_b32 s44, s28, s1
	s_add_i32 s33, 0, 0x14000
	v_add_u32_e32 v142, s62, v240
	v_add_u32_e32 v158, s33, v240
	ds_read_b128 v[130:133], v142
	ds_read_b128 v[134:137], v142 offset:1024
	ds_read_b128 v[138:141], v142 offset:2048
	ds_read_b128 v[142:145], v142 offset:3072
	ds_read_b128 v[146:149], v158
	ds_read_b128 v[150:153], v158 offset:1024
	ds_read_b128 v[154:157], v158 offset:2048
	ds_read_b128 v[158:161], v158 offset:3072
	s_add_u32 s100, s1, s41
	s_addc_u32 s101, s4, 0
	s_sub_u32 s100, s100, 0x80
	s_subb_u32 s101, s101, 0
	v_lshl_add_u64 v[212:213], s[100:101], 0, v[48:49]
	s_add_i32 m0, s82, 0x1c000
	s_nop 0
	global_load_lds_dwordx4 v[212:213], off
	v_lshl_add_u64 v[212:213], s[100:101], 0, v[198:199]
	s_add_i32 m0, s82, 0x1e000
	s_nop 0
	global_load_lds_dwordx4 v[212:213], off
	v_lshl_add_u64 v[212:213], s[34:35], 0, v[204:205]
	s_add_i32 m0, s82, 0xc000
	ds_read_b128 v[162:165], v242
	ds_read_b128 v[166:169], v242 offset:1024
	ds_read_b128 v[170:173], v242 offset:2048
	ds_read_b128 v[174:177], v242 offset:3072
	ds_read_b128 v[178:181], v242 offset:4096
	ds_read_b128 v[182:185], v242 offset:5120
	ds_read_b128 v[186:189], v242 offset:6144
	ds_read_b128 v[208:211], v242 offset:7168
	global_load_lds_dwordx4 v[212:213], off
	v_lshl_add_u64 v[212:213], s[34:35], 0, v[206:207]
	s_add_i32 m0, s82, 0xe000
	s_nop 0
	global_load_lds_dwordx4 v[212:213], off
	s_waitcnt vmcnt(8)
	s_waitcnt lgkmcnt(0)
	s_barrier
	s_setprio 1
	s_waitcnt lgkmcnt(0)
	v_mfma_f32_16x16x32_bf16 v[126:129], v[130:133], v[162:165], v[126:129]
	v_mfma_f32_16x16x32_bf16 v[122:125], v[138:141], v[162:165], v[122:125]
	v_mfma_f32_16x16x32_bf16 v[110:113], v[130:133], v[170:173], v[110:113]
	v_mfma_f32_16x16x32_bf16 v[98:101], v[138:141], v[170:173], v[98:101]
	v_mfma_f32_16x16x32_bf16 v[94:97], v[130:133], v[178:181], v[94:97]
	v_mfma_f32_16x16x32_bf16 v[82:85], v[138:141], v[178:181], v[82:85]
	v_mfma_f32_16x16x32_bf16 v[78:81], v[130:133], v[186:189], v[78:81]
	v_mfma_f32_16x16x32_bf16 v[66:69], v[138:141], v[186:189], v[66:69]
	v_mfma_f32_16x16x32_bf16 v[126:129], v[134:137], v[166:169], v[126:129]
	v_mfma_f32_16x16x32_bf16 v[122:125], v[142:145], v[166:169], v[122:125]
	v_mfma_f32_16x16x32_bf16 v[110:113], v[134:137], v[174:177], v[110:113]
	v_mfma_f32_16x16x32_bf16 v[98:101], v[142:145], v[174:177], v[98:101]
	v_mfma_f32_16x16x32_bf16 v[94:97], v[134:137], v[182:185], v[94:97]
	v_mfma_f32_16x16x32_bf16 v[82:85], v[142:145], v[182:185], v[82:85]
	v_mfma_f32_16x16x32_bf16 v[78:81], v[134:137], v[208:211], v[78:81]
	v_mfma_f32_16x16x32_bf16 v[66:69], v[142:145], v[208:211], v[66:69]
	s_setprio 0
	s_setprio 1
	v_mfma_f32_16x16x32_bf16 v[118:121], v[146:149], v[162:165], v[118:121]
	v_mfma_f32_16x16x32_bf16 v[114:117], v[154:157], v[162:165], v[114:117]
	v_mfma_f32_16x16x32_bf16 v[106:109], v[146:149], v[170:173], v[106:109]
	v_mfma_f32_16x16x32_bf16 v[102:105], v[154:157], v[170:173], v[102:105]
	v_mfma_f32_16x16x32_bf16 v[90:93], v[146:149], v[178:181], v[90:93]
	v_mfma_f32_16x16x32_bf16 v[86:89], v[154:157], v[178:181], v[86:89]
	v_mfma_f32_16x16x32_bf16 v[74:77], v[146:149], v[186:189], v[74:77]
	v_mfma_f32_16x16x32_bf16 v[70:73], v[154:157], v[186:189], v[70:73]
	v_mfma_f32_16x16x32_bf16 v[118:121], v[150:153], v[166:169], v[118:121]
	v_mfma_f32_16x16x32_bf16 v[114:117], v[158:161], v[166:169], v[114:117]
	v_mfma_f32_16x16x32_bf16 v[106:109], v[150:153], v[174:177], v[106:109]
	v_mfma_f32_16x16x32_bf16 v[102:105], v[158:161], v[174:177], v[102:105]
	v_mfma_f32_16x16x32_bf16 v[90:93], v[150:153], v[182:185], v[90:93]
	v_mfma_f32_16x16x32_bf16 v[86:89], v[158:161], v[182:185], v[86:89]
	v_mfma_f32_16x16x32_bf16 v[74:77], v[150:153], v[208:211], v[74:77]
	v_mfma_f32_16x16x32_bf16 v[70:73], v[158:161], v[208:211], v[70:73]
	s_setprio 0
	s_barrier
	s_add_i32 s46, s62, s52
	v_lshl_add_u64 v[212:213], s[44:45], 0, v[48:49]
	s_mov_b32 m0, s46
	ds_read_b128 v[162:165], v242 offset:16384
	ds_read_b128 v[166:169], v242 offset:17408
	ds_read_b128 v[170:173], v242 offset:18432
	ds_read_b128 v[174:177], v242 offset:19456
	ds_read_b128 v[178:181], v242 offset:20480
	ds_read_b128 v[182:185], v242 offset:21504
	ds_read_b128 v[186:189], v242 offset:22528
	ds_read_b128 v[208:211], v242 offset:23552
	global_load_lds_dwordx4 v[212:213], off
	s_add_i32 m0, s46, 0x2000
	v_lshl_add_u64 v[214:215], s[44:45], 0, v[198:199]
	s_add_u32 s44, s44, s41
	s_addc_u32 s45, s45, 0
	s_add_i32 s33, s33, s52
	global_load_lds_dwordx4 v[214:215], off
	v_lshl_add_u64 v[216:217], s[44:45], 0, v[48:49]
	v_lshl_add_u64 v[218:219], s[44:45], 0, v[198:199]
	v_lshl_add_u64 v[220:221], s[30:31], 0, v[202:203]
	s_mov_b32 m0, s82
	v_lshl_add_u64 v[222:223], s[30:31], 0, v[200:201]
	global_load_lds_dwordx4 v[220:221], off
	s_mov_b32 m0, s83
	s_nop 0
	global_load_lds_dwordx4 v[222:223], off
	s_waitcnt vmcnt(6)
	s_waitcnt lgkmcnt(0)
	s_barrier
	s_setprio 1
	s_waitcnt lgkmcnt(0)
	v_mfma_f32_16x16x32_bf16 v[62:65], v[130:133], v[162:165], v[62:65]
	v_mfma_f32_16x16x32_bf16 v[50:53], v[138:141], v[162:165], v[50:53]
	v_mfma_f32_16x16x32_bf16 v[44:47], v[130:133], v[170:173], v[44:47]
	v_mfma_f32_16x16x32_bf16 v[32:35], v[138:141], v[170:173], v[32:35]
	v_mfma_f32_16x16x32_bf16 v[28:31], v[130:133], v[178:181], v[28:31]
	v_mfma_f32_16x16x32_bf16 v[16:19], v[138:141], v[178:181], v[16:19]
	v_mfma_f32_16x16x32_bf16 v[12:15], v[130:133], v[186:189], v[12:15]
	v_mfma_f32_16x16x32_bf16 v[0:3], v[138:141], v[186:189], v[0:3]
	v_mfma_f32_16x16x32_bf16 v[62:65], v[134:137], v[166:169], v[62:65]
	v_mfma_f32_16x16x32_bf16 v[50:53], v[142:145], v[166:169], v[50:53]
	v_mfma_f32_16x16x32_bf16 v[44:47], v[134:137], v[174:177], v[44:47]
	v_mfma_f32_16x16x32_bf16 v[32:35], v[142:145], v[174:177], v[32:35]
	v_mfma_f32_16x16x32_bf16 v[28:31], v[134:137], v[182:185], v[28:31]
	v_mfma_f32_16x16x32_bf16 v[16:19], v[142:145], v[182:185], v[16:19]
	v_mfma_f32_16x16x32_bf16 v[12:15], v[134:137], v[208:211], v[12:15]
	v_mfma_f32_16x16x32_bf16 v[0:3], v[142:145], v[208:211], v[0:3]
	s_setprio 0
	s_setprio 1
	v_mfma_f32_16x16x32_bf16 v[58:61], v[146:149], v[162:165], v[58:61]
	v_mfma_f32_16x16x32_bf16 v[54:57], v[154:157], v[162:165], v[54:57]
	v_mfma_f32_16x16x32_bf16 v[40:43], v[146:149], v[170:173], v[40:43]
	v_mfma_f32_16x16x32_bf16 v[36:39], v[154:157], v[170:173], v[36:39]
	v_mfma_f32_16x16x32_bf16 v[24:27], v[146:149], v[178:181], v[24:27]
	v_mfma_f32_16x16x32_bf16 v[20:23], v[154:157], v[178:181], v[20:23]
	v_mfma_f32_16x16x32_bf16 v[8:11], v[146:149], v[186:189], v[8:11]
	v_mfma_f32_16x16x32_bf16 v[4:7], v[154:157], v[186:189], v[4:7]
	v_mfma_f32_16x16x32_bf16 v[58:61], v[150:153], v[166:169], v[58:61]
	v_mfma_f32_16x16x32_bf16 v[54:57], v[158:161], v[166:169], v[54:57]
	v_mfma_f32_16x16x32_bf16 v[40:43], v[150:153], v[174:177], v[40:43]
	v_mfma_f32_16x16x32_bf16 v[36:39], v[158:161], v[174:177], v[36:39]
	v_mfma_f32_16x16x32_bf16 v[24:27], v[150:153], v[182:185], v[24:27]
	v_mfma_f32_16x16x32_bf16 v[20:23], v[158:161], v[182:185], v[20:23]
	v_mfma_f32_16x16x32_bf16 v[8:11], v[150:153], v[208:211], v[8:11]
	v_mfma_f32_16x16x32_bf16 v[4:7], v[158:161], v[208:211], v[4:7]
	s_setprio 0
	s_barrier
	s_add_i32 s33, 0, 0x18000
	s_add_i32 s44, 0, 0x1c000
	v_add_u32_e32 v142, s33, v240
	v_add_u32_e32 v158, s44, v240
	ds_read_b128 v[130:133], v142
	ds_read_b128 v[134:137], v142 offset:1024
	ds_read_b128 v[138:141], v142 offset:2048
	ds_read_b128 v[142:145], v142 offset:3072
	ds_read_b128 v[146:149], v158
	ds_read_b128 v[150:153], v158 offset:1024
	ds_read_b128 v[154:157], v158 offset:2048
	ds_read_b128 v[158:161], v158 offset:3072
	s_add_i32 m0, s82, 0x14000
	s_nop 0
	global_load_lds_dwordx4 v[216:217], off
	s_add_i32 m0, s82, 0x16000
	s_nop 0
	global_load_lds_dwordx4 v[218:219], off
	s_add_u32 s30, s30, s50
	s_addc_u32 s31, s31, 0
	s_mov_b32 m0, s84
	v_lshl_add_u64 v[224:225], s[30:31], 0, v[202:203]
	ds_read_b128 v[162:165], v242 offset:32768
	ds_read_b128 v[166:169], v242 offset:33792
	ds_read_b128 v[170:173], v242 offset:34816
	ds_read_b128 v[174:177], v242 offset:35840
	ds_read_b128 v[178:181], v242 offset:36864
	ds_read_b128 v[182:185], v242 offset:37888
	ds_read_b128 v[186:189], v242 offset:38912
	ds_read_b128 v[208:211], v242 offset:39936
	global_load_lds_dwordx4 v[224:225], off
	v_lshl_add_u64 v[224:225], s[30:31], 0, v[200:201]
	s_mov_b32 m0, s85
	s_nop 0
	global_load_lds_dwordx4 v[224:225], off
	s_waitcnt vmcnt(8)
	s_waitcnt lgkmcnt(0)
	s_barrier
	s_setprio 1
	s_waitcnt lgkmcnt(0)
	v_mfma_f32_16x16x32_bf16 v[126:129], v[130:133], v[162:165], v[126:129]
	v_mfma_f32_16x16x32_bf16 v[122:125], v[138:141], v[162:165], v[122:125]
	v_mfma_f32_16x16x32_bf16 v[110:113], v[130:133], v[170:173], v[110:113]
	v_mfma_f32_16x16x32_bf16 v[98:101], v[138:141], v[170:173], v[98:101]
	v_mfma_f32_16x16x32_bf16 v[94:97], v[130:133], v[178:181], v[94:97]
	v_mfma_f32_16x16x32_bf16 v[82:85], v[138:141], v[178:181], v[82:85]
	v_mfma_f32_16x16x32_bf16 v[78:81], v[130:133], v[186:189], v[78:81]
	v_mfma_f32_16x16x32_bf16 v[66:69], v[138:141], v[186:189], v[66:69]
	v_mfma_f32_16x16x32_bf16 v[126:129], v[134:137], v[166:169], v[126:129]
	v_mfma_f32_16x16x32_bf16 v[122:125], v[142:145], v[166:169], v[122:125]
	v_mfma_f32_16x16x32_bf16 v[110:113], v[134:137], v[174:177], v[110:113]
	v_mfma_f32_16x16x32_bf16 v[98:101], v[142:145], v[174:177], v[98:101]
	v_mfma_f32_16x16x32_bf16 v[94:97], v[134:137], v[182:185], v[94:97]
	v_mfma_f32_16x16x32_bf16 v[82:85], v[142:145], v[182:185], v[82:85]
	v_mfma_f32_16x16x32_bf16 v[78:81], v[134:137], v[208:211], v[78:81]
	v_mfma_f32_16x16x32_bf16 v[66:69], v[142:145], v[208:211], v[66:69]
	s_setprio 0
	s_setprio 1
	v_mfma_f32_16x16x32_bf16 v[118:121], v[146:149], v[162:165], v[118:121]
	v_mfma_f32_16x16x32_bf16 v[114:117], v[154:157], v[162:165], v[114:117]
	v_mfma_f32_16x16x32_bf16 v[106:109], v[146:149], v[170:173], v[106:109]
	v_mfma_f32_16x16x32_bf16 v[102:105], v[154:157], v[170:173], v[102:105]
	v_mfma_f32_16x16x32_bf16 v[90:93], v[146:149], v[178:181], v[90:93]
	v_mfma_f32_16x16x32_bf16 v[86:89], v[154:157], v[178:181], v[86:89]
	v_mfma_f32_16x16x32_bf16 v[74:77], v[146:149], v[186:189], v[74:77]
	v_mfma_f32_16x16x32_bf16 v[70:73], v[154:157], v[186:189], v[70:73]
	v_mfma_f32_16x16x32_bf16 v[118:121], v[150:153], v[166:169], v[118:121]
	v_mfma_f32_16x16x32_bf16 v[114:117], v[158:161], v[166:169], v[114:117]
	v_mfma_f32_16x16x32_bf16 v[106:109], v[150:153], v[174:177], v[106:109]
	v_mfma_f32_16x16x32_bf16 v[102:105], v[158:161], v[174:177], v[102:105]
	v_mfma_f32_16x16x32_bf16 v[90:93], v[150:153], v[182:185], v[90:93]
	v_mfma_f32_16x16x32_bf16 v[86:89], v[158:161], v[182:185], v[86:89]
	v_mfma_f32_16x16x32_bf16 v[74:77], v[150:153], v[208:211], v[74:77]
	v_mfma_f32_16x16x32_bf16 v[70:73], v[158:161], v[208:211], v[70:73]
	s_setprio 0
	s_barrier
	s_add_i32 s30, s33, s52
	v_lshl_add_u64 v[212:213], v[212:213], 0, s[70:71]
	s_mov_b32 m0, s30
	ds_read_b128 v[162:165], v242 offset:49152
	ds_read_b128 v[166:169], v242 offset:50176
	ds_read_b128 v[170:173], v242 offset:51200
	ds_read_b128 v[174:177], v242 offset:52224
	ds_read_b128 v[178:181], v242 offset:53248
	ds_read_b128 v[182:185], v242 offset:54272
	ds_read_b128 v[186:189], v242 offset:55296
	ds_read_b128 v[208:211], v242 offset:56320
	global_load_lds_dwordx4 v[212:213], off
	v_lshl_add_u64 v[212:213], v[214:215], 0, s[70:71]
	s_add_i32 m0, s30, 0x2000
	s_add_i32 s30, s44, s52
	global_load_lds_dwordx4 v[212:213], off
	v_lshl_add_u64 v[212:213], v[220:221], 0, s[70:71]
	s_mov_b32 m0, s86
	s_nop 0
	global_load_lds_dwordx4 v[212:213], off
	v_lshl_add_u64 v[212:213], v[222:223], 0, s[70:71]
	s_mov_b32 m0, s87
	s_nop 0
	global_load_lds_dwordx4 v[212:213], off
	s_waitcnt vmcnt(6)
	s_waitcnt lgkmcnt(0)
	s_barrier
	s_setprio 1
	s_waitcnt lgkmcnt(0)
	v_mfma_f32_16x16x32_bf16 v[62:65], v[130:133], v[162:165], v[62:65]
	v_mfma_f32_16x16x32_bf16 v[50:53], v[138:141], v[162:165], v[50:53]
	v_mfma_f32_16x16x32_bf16 v[44:47], v[130:133], v[170:173], v[44:47]
	v_mfma_f32_16x16x32_bf16 v[32:35], v[138:141], v[170:173], v[32:35]
	v_mfma_f32_16x16x32_bf16 v[28:31], v[130:133], v[178:181], v[28:31]
	v_mfma_f32_16x16x32_bf16 v[16:19], v[138:141], v[178:181], v[16:19]
	v_mfma_f32_16x16x32_bf16 v[12:15], v[130:133], v[186:189], v[12:15]
	v_mfma_f32_16x16x32_bf16 v[0:3], v[138:141], v[186:189], v[0:3]
	v_mfma_f32_16x16x32_bf16 v[62:65], v[134:137], v[166:169], v[62:65]
	v_mfma_f32_16x16x32_bf16 v[50:53], v[142:145], v[166:169], v[50:53]
	v_mfma_f32_16x16x32_bf16 v[44:47], v[134:137], v[174:177], v[44:47]
	v_mfma_f32_16x16x32_bf16 v[32:35], v[142:145], v[174:177], v[32:35]
	v_mfma_f32_16x16x32_bf16 v[28:31], v[134:137], v[182:185], v[28:31]
	v_mfma_f32_16x16x32_bf16 v[16:19], v[142:145], v[182:185], v[16:19]
	v_mfma_f32_16x16x32_bf16 v[12:15], v[134:137], v[208:211], v[12:15]
	v_mfma_f32_16x16x32_bf16 v[0:3], v[142:145], v[208:211], v[0:3]
	s_setprio 0
	s_setprio 1
	v_mfma_f32_16x16x32_bf16 v[58:61], v[146:149], v[162:165], v[58:61]
	v_mfma_f32_16x16x32_bf16 v[54:57], v[154:157], v[162:165], v[54:57]
	v_mfma_f32_16x16x32_bf16 v[40:43], v[146:149], v[170:173], v[40:43]
	v_mfma_f32_16x16x32_bf16 v[36:39], v[154:157], v[170:173], v[36:39]
	v_mfma_f32_16x16x32_bf16 v[24:27], v[146:149], v[178:181], v[24:27]
	v_mfma_f32_16x16x32_bf16 v[20:23], v[154:157], v[178:181], v[20:23]
	v_mfma_f32_16x16x32_bf16 v[8:11], v[146:149], v[186:189], v[8:11]
	v_mfma_f32_16x16x32_bf16 v[4:7], v[154:157], v[186:189], v[4:7]
	v_mfma_f32_16x16x32_bf16 v[58:61], v[150:153], v[166:169], v[58:61]
	v_mfma_f32_16x16x32_bf16 v[54:57], v[158:161], v[166:169], v[54:57]
	v_mfma_f32_16x16x32_bf16 v[40:43], v[150:153], v[174:177], v[40:43]
	v_mfma_f32_16x16x32_bf16 v[36:39], v[158:161], v[174:177], v[36:39]
	v_mfma_f32_16x16x32_bf16 v[24:27], v[150:153], v[182:185], v[24:27]
	v_mfma_f32_16x16x32_bf16 v[20:23], v[158:161], v[182:185], v[20:23]
	v_mfma_f32_16x16x32_bf16 v[8:11], v[150:153], v[208:211], v[8:11]
	v_mfma_f32_16x16x32_bf16 v[4:7], v[158:161], v[208:211], v[4:7]
	s_setprio 0
	s_barrier
	s_add_u32 s34, s34, 0x100
	s_addc_u32 s35, s35, 0
	s_add_u32 s1, s1, 0x100
	s_addc_u32 s4, s4, 0
	s_cmp_ge_u32 s27, s89
	s_mov_b32 s30, s27
	s_cbranch_scc0 .LBB0_194
	s_and_b64 vcc, exec, s[24:25]
	s_cbranch_vccz .LBB0_197
	s_barrier
